# attention main loops: issue V DMA pieces before the (now contiguous) K piece
# speedup vs baseline: 1.0027x; 1.0027x over previous
.LBB0_644:
	v_add_u32_e32 v181, s44, v203
	v_lshl_add_u64 v[188:189], v[182:183], 0, s[42:43]
	s_mov_b64 s[44:45], 0x15204000
	v_lshl_add_u64 v[110:111], v[188:189], 0, s[44:45]
	s_add_i32 s44, s68, s49
	s_mov_b32 m0, s44
	s_nop 0
	global_load_lds_dwordx4 v[110:111], off
	v_lshl_add_u64 v[186:187], v[184:185], 0, s[42:43]
	v_lshl_add_u64 v[110:111], v[186:187], 0, s[76:77]
	s_add_i32 s44, s70, s35
	s_mov_b32 m0, s44
	s_nop 0
	global_load_lds_dwordx4 v[110:111], off
	ds_read_b64_tr_b16 v[176:177], v181 offset:24576
	ds_read_b64_tr_b16 v[178:179], v181 offset:25088
	v_mfma_f32_32x32x16_bf16 v[96:111], v[172:175], v[140:143], v[32:47]
	v_add_f32_e32 v80, v64, v65
	v_add_f32_e32 v80, v66, v80
	v_add_f32_e32 v80, v67, v80
	v_add_f32_e32 v80, v68, v80
	v_add_f32_e32 v80, v69, v80
	v_cvt_pk_bf16_f32 v136, v64, v65
	v_cvt_pk_bf16_f32 v137, v66, v67
	ds_read_b64_tr_b16 v[172:173], v181 offset:28672
	ds_read_b64_tr_b16 v[174:175], v181 offset:29184
	v_add_f32_e32 v64, v70, v80
	v_mfma_f32_32x32x16_bf16 v[80:95], v[168:171], v[140:143], v[32:47]
	v_add_f32_e32 v64, v71, v64
	v_add_f32_e32 v64, v72, v64
	v_add_f32_e32 v116, v73, v64
	v_cvt_pk_bf16_f32 v138, v68, v69
	v_cvt_pk_bf16_f32 v139, v70, v71
	ds_read_b64_tr_b16 v[64:65], v181 offset:25600
	ds_read_b64_tr_b16 v[66:67], v181 offset:26112
	v_mfma_f32_32x32x16_bf16 v[96:111], v[164:167], v[132:135], v[96:111]
	v_add_f32_e32 v68, v74, v116
	v_add_f32_e32 v68, v75, v68
	v_add_f32_e32 v68, v76, v68
	v_add_f32_e32 v116, v77, v68
	v_cvt_pk_bf16_f32 v128, v72, v73
	v_cvt_pk_bf16_f32 v129, v74, v75
	ds_read_b64_tr_b16 v[68:69], v181 offset:29696
	ds_read_b64_tr_b16 v[70:71], v181 offset:30208
	v_mfma_f32_32x32x16_bf16 v[80:95], v[160:163], v[132:135], v[80:95]
	v_add_f32_e32 v72, v78, v116
	v_add_f32_e32 v72, v79, v72
	v_add_f32_e32 v72, v48, v72
	v_add_f32_e32 v116, v49, v72
	v_cvt_pk_bf16_f32 v130, v76, v77
	v_cvt_pk_bf16_f32 v131, v78, v79
	ds_read_b64_tr_b16 v[72:73], v181 offset:26624
	ds_read_b64_tr_b16 v[74:75], v181 offset:27136
	v_mfma_f32_32x32x16_bf16 v[96:111], v[156:159], v[120:123], v[96:111]
	v_add_f32_e32 v76, v50, v116
	v_add_f32_e32 v76, v51, v76
	v_add_f32_e32 v76, v52, v76
	v_add_f32_e32 v76, v53, v76
	v_cvt_pk_bf16_f32 v124, v48, v49
	v_cvt_pk_bf16_f32 v125, v50, v51
	ds_read_b64_tr_b16 v[48:49], v181 offset:30720
	ds_read_b64_tr_b16 v[50:51], v181 offset:31232
	v_mfma_f32_32x32x16_bf16 v[80:95], v[152:155], v[120:123], v[80:95]
	v_add_f32_e32 v76, v54, v76
	v_add_f32_e32 v76, v55, v76
	v_add_f32_e32 v76, v56, v76
	v_add_f32_e32 v76, v57, v76
	v_cvt_pk_bf16_f32 v126, v52, v53
	v_cvt_pk_bf16_f32 v127, v54, v55
	ds_read_b64_tr_b16 v[52:53], v181 offset:27648
	ds_read_b64_tr_b16 v[54:55], v181 offset:28160
	v_mfma_f32_32x32x16_bf16 v[96:111], v[148:151], v[112:115], v[96:111]
	v_add_f32_e32 v76, v58, v76
	v_add_f32_e32 v76, v59, v76
	v_add_f32_e32 v76, v60, v76
	v_add_f32_e32 v76, v61, v76
	v_cvt_pk_bf16_f32 v116, v56, v57
	v_cvt_pk_bf16_f32 v117, v58, v59
	ds_read_b64_tr_b16 v[56:57], v181 offset:31744
	ds_read_b64_tr_b16 v[58:59], v181 offset:32256
	v_mfma_f32_32x32x16_bf16 v[80:95], v[144:147], v[112:115], v[80:95]
	v_add_f32_e32 v76, v62, v76
	v_add_f32_e32 v76, v63, v76
	v_cvt_pk_bf16_f32 v118, v60, v61
	v_cvt_pk_bf16_f32 v119, v62, v63
	v_add_f32_e32 v191, v192, v76
	v_max_f32_e32 v60, v96, v97
	v_max3_f32 v61, v98, v99, v100
	v_max3_f32 v60, v60, v102, v103
	v_max3_f32 v61, v61, v101, v104
	v_max3_f32 v60, v60, v106, v107
	v_max3_f32 v61, v61, v105, v108
	v_max3_f32 v60, v60, v110, v111
	s_nop 0
	v_max3_f32 v61, v61, v109, v81
	v_max3_f32 v60, v60, v80, v82
	v_max3_f32 v61, v61, v83, v84
	v_max3_f32 v60, v60, v86, v87
	v_max3_f32 v61, v61, v85, v88
	v_max3_f32 v60, v60, v90, v91
	v_max3_f32 v61, v61, v89, v92
	v_max3_f32 v60, v60, v94, v95
	v_max3_f32 v60, v60, v93, v61
	v_mov_b32_e32 v61, v60
	s_nop 1
	v_permlane32_swap_b32_e32 v60, v61
	v_max_f32_e32 v60, v60, v61
	v_cmp_lt_f32_e32 vcc, s29, v60
	s_cmp_lg_u64 vcc, 0
	s_cselect_b64 s[44:45], -1, 0
	s_cbranch_vccnz .LBB0_652

.LBB0_647:
	s_add_i32 s44, s68, 0x2000
	s_cmpk_lg_i32 s68, 0x4000
	s_cselect_b32 s60, s44, 0
	s_mov_b64 s[44:45], 0x15206000
	v_lshl_add_u64 v[78:79], v[188:189], 0, s[44:45]
	s_add_i32 s44, s60, s49
	s_mov_b32 m0, s44
	s_nop 0
	global_load_lds_dwordx4 v[78:79], off
	s_mov_b64 s[44:45], 0x1490a000
	v_lshl_add_u64 v[78:79], v[186:187], 0, s[44:45]
	s_add_i32 s44, s68, s35
	s_mov_b32 m0, s44
	s_nop 0
	global_load_lds_dwordx4 v[78:79], off
	v_add_u32_e32 v192, s70, v203
	ds_read_b64_tr_b16 v[148:149], v192 offset:24576
	ds_read_b64_tr_b16 v[150:151], v192 offset:25088
	v_mfma_f32_32x32x16_bf16 v[64:79], v[60:63], v[140:143], v[32:47]
	v_add_f32_e32 v48, v96, v97
	v_add_f32_e32 v48, v98, v48
	v_add_f32_e32 v48, v99, v48
	v_add_f32_e32 v48, v100, v48
	v_add_f32_e32 v48, v101, v48
	v_cvt_pk_bf16_f32 v136, v96, v97
	v_cvt_pk_bf16_f32 v137, v98, v99
	ds_read_b64_tr_b16 v[144:145], v192 offset:28672
	ds_read_b64_tr_b16 v[146:147], v192 offset:29184
	v_add_f32_e32 v48, v102, v48
	v_add_f32_e32 v48, v103, v48
	v_add_f32_e32 v48, v104, v48
	v_add_f32_e32 v116, v105, v48
	v_mfma_f32_32x32x16_bf16 v[48:63], v[172:175], v[140:143], v[32:47]
	v_cvt_pk_bf16_f32 v138, v100, v101
	v_cvt_pk_bf16_f32 v139, v102, v103
	ds_read_b64_tr_b16 v[96:97], v192 offset:25600
	ds_read_b64_tr_b16 v[98:99], v192 offset:26112
	v_mfma_f32_32x32x16_bf16 v[64:79], v[176:179], v[132:135], v[64:79]
	v_add_f32_e32 v100, v106, v116
	v_add_f32_e32 v100, v107, v100
	v_add_f32_e32 v100, v108, v100
	v_add_f32_e32 v116, v109, v100
	v_cvt_pk_bf16_f32 v128, v104, v105
	v_cvt_pk_bf16_f32 v129, v106, v107
	ds_read_b64_tr_b16 v[100:101], v192 offset:29696
	ds_read_b64_tr_b16 v[102:103], v192 offset:30208
	v_mfma_f32_32x32x16_bf16 v[48:63], v[168:171], v[132:135], v[48:63]
	v_add_f32_e32 v104, v110, v116
	v_add_f32_e32 v104, v111, v104
	v_add_f32_e32 v104, v80, v104
	v_add_f32_e32 v116, v81, v104
	v_cvt_pk_bf16_f32 v130, v108, v109
	v_cvt_pk_bf16_f32 v131, v110, v111
	ds_read_b64_tr_b16 v[104:105], v192 offset:26624
	ds_read_b64_tr_b16 v[106:107], v192 offset:27136
	v_mfma_f32_32x32x16_bf16 v[64:79], v[164:167], v[120:123], v[64:79]
	v_add_f32_e32 v108, v82, v116
	v_add_f32_e32 v108, v83, v108
	v_add_f32_e32 v108, v84, v108
	v_add_f32_e32 v108, v85, v108
	v_cvt_pk_bf16_f32 v124, v80, v81
	v_cvt_pk_bf16_f32 v125, v82, v83
	ds_read_b64_tr_b16 v[80:81], v192 offset:30720
	ds_read_b64_tr_b16 v[82:83], v192 offset:31232
	v_mfma_f32_32x32x16_bf16 v[48:63], v[160:163], v[120:123], v[48:63]
	v_add_f32_e32 v108, v86, v108
	v_add_f32_e32 v108, v87, v108
	v_add_f32_e32 v108, v88, v108
	v_add_f32_e32 v108, v89, v108
	v_cvt_pk_bf16_f32 v126, v84, v85
	v_cvt_pk_bf16_f32 v127, v86, v87
	ds_read_b64_tr_b16 v[84:85], v192 offset:27648
	ds_read_b64_tr_b16 v[86:87], v192 offset:28160
	v_mfma_f32_32x32x16_bf16 v[64:79], v[156:159], v[112:115], v[64:79]
	v_add_f32_e32 v108, v90, v108
	v_add_f32_e32 v108, v91, v108
	v_add_f32_e32 v108, v92, v108
	v_add_f32_e32 v108, v93, v108
	v_cvt_pk_bf16_f32 v116, v88, v89
	v_cvt_pk_bf16_f32 v117, v90, v91
	ds_read_b64_tr_b16 v[88:89], v192 offset:31744
	ds_read_b64_tr_b16 v[90:91], v192 offset:32256
	v_mfma_f32_32x32x16_bf16 v[48:63], v[152:155], v[112:115], v[48:63]
	v_add_f32_e32 v108, v94, v108
	v_add_f32_e32 v108, v95, v108
	v_cvt_pk_bf16_f32 v118, v92, v93
	v_cvt_pk_bf16_f32 v119, v94, v95
	v_add_f32_e32 v192, v191, v108
	v_max_f32_e32 v92, v64, v65
	v_max3_f32 v93, v66, v67, v68
	v_max3_f32 v92, v92, v70, v71
	v_max3_f32 v93, v93, v69, v72
	v_max3_f32 v92, v92, v74, v75
	v_max3_f32 v93, v93, v73, v76
	v_max3_f32 v92, v92, v78, v79
	s_nop 0
	v_max3_f32 v93, v93, v77, v49
	v_max3_f32 v92, v92, v48, v50
	v_max3_f32 v93, v93, v51, v52
	v_max3_f32 v92, v92, v54, v55
	v_max3_f32 v93, v93, v53, v56
	v_max3_f32 v92, v92, v58, v59
	v_max3_f32 v93, v93, v57, v60
	v_max3_f32 v92, v92, v62, v63
	v_max3_f32 v92, v92, v61, v93
	v_mov_b32_e32 v93, v92
	s_nop 1
	v_permlane32_swap_b32_e32 v92, v93
	v_max_f32_e32 v92, v92, v93
	v_cmp_lt_f32_e32 vcc, s29, v92
	s_cmp_lg_u64 vcc, 0
	s_cselect_b64 s[44:45], -1, 0
	s_cbranch_vccnz .LBB0_655

.LBB0_721:
	s_movk_i32 s42, 0xbf80
	s_mov_b32 s43, -1
	v_lshl_add_u64 v[142:143], v[212:213], 0, s[42:43]
	s_lshl_b32 s42, s61, 1
	s_add_i32 s44, s42, s60
	s_mov_b32 m0, s44
	s_nop 0
	global_load_lds_dwordx4 v[142:143], off
	s_movk_i32 s42, 0xc000
	s_mov_b32 s43, -1
	v_lshl_add_u64 v[142:143], v[212:213], 0, s[42:43]
	s_add_i32 s42, s44, 0x2000
	s_mov_b32 m0, s42
	s_nop 0
	global_load_lds_dwordx4 v[142:143], off
	s_movk_i32 s42, 0xe000
	s_mov_b32 s43, -1
	v_lshl_add_u64 v[142:143], v[214:215], 0, s[42:43]
	s_add_i32 s42, s71, s49
	s_mov_b32 m0, s42
	s_nop 0
	global_load_lds_dwordx4 v[142:143], off
	v_mfma_f32_32x32x16_bf16 v[128:143], v[204:207], v[172:175], v[64:79]
	v_add_f32_e32 v112, v96, v97
	v_add_f32_e32 v112, v98, v112
	v_add_f32_e32 v112, v99, v112
	v_add_f32_e32 v112, v100, v112
	v_add_f32_e32 v112, v101, v112
	v_cvt_pk_bf16_f32 v160, v96, v97
	v_cvt_pk_bf16_f32 v161, v98, v99
	v_add_f32_e32 v96, v102, v112
	v_mfma_f32_32x32x16_bf16 v[112:127], v[200:203], v[172:175], v[64:79]
	v_add_f32_e32 v96, v103, v96
	v_add_f32_e32 v96, v104, v96
	v_add_f32_e32 v96, v105, v96
	v_cvt_pk_bf16_f32 v162, v100, v101
	v_cvt_pk_bf16_f32 v163, v102, v103
	v_mfma_f32_32x32x16_bf16 v[128:143], v[196:199], v[168:171], v[128:143]
	v_add_f32_e32 v96, v106, v96
	v_add_f32_e32 v96, v107, v96
	v_add_f32_e32 v96, v108, v96
	v_add_f32_e32 v96, v109, v96
	v_cvt_pk_bf16_f32 v152, v104, v105
	v_cvt_pk_bf16_f32 v153, v106, v107
	v_mfma_f32_32x32x16_bf16 v[112:127], v[192:195], v[168:171], v[112:127]
	v_add_f32_e32 v96, v110, v96
	v_add_f32_e32 v96, v111, v96
	v_add_f32_e32 v96, v80, v96
	v_add_f32_e32 v96, v81, v96
	v_cvt_pk_bf16_f32 v154, v108, v109
	v_cvt_pk_bf16_f32 v155, v110, v111
	v_mfma_f32_32x32x16_bf16 v[128:143], v[188:191], v[164:167], v[128:143]
	v_add_f32_e32 v96, v82, v96
	v_add_f32_e32 v96, v83, v96
	v_add_f32_e32 v96, v84, v96
	v_add_f32_e32 v96, v85, v96
	v_cvt_pk_bf16_f32 v148, v80, v81
	v_cvt_pk_bf16_f32 v149, v82, v83
	v_mfma_f32_32x32x16_bf16 v[112:127], v[184:187], v[164:167], v[112:127]
	v_add_f32_e32 v80, v86, v96
	v_add_f32_e32 v80, v87, v80
	v_add_f32_e32 v80, v88, v80
	v_add_f32_e32 v80, v89, v80
	v_cvt_pk_bf16_f32 v150, v84, v85
	v_cvt_pk_bf16_f32 v151, v86, v87
	v_mfma_f32_32x32x16_bf16 v[128:143], v[180:183], v[156:159], v[128:143]
	v_add_f32_e32 v80, v90, v80
	v_add_f32_e32 v80, v91, v80
	v_add_f32_e32 v80, v92, v80
	v_add_f32_e32 v80, v93, v80
	v_cvt_pk_bf16_f32 v144, v88, v89
	v_cvt_pk_bf16_f32 v145, v90, v91
	v_mfma_f32_32x32x16_bf16 v[112:127], v[176:179], v[156:159], v[112:127]
	v_add_f32_e32 v80, v94, v80
	v_add_f32_e32 v82, v95, v80
	v_cvt_pk_bf16_f32 v146, v92, v93
	v_cvt_pk_bf16_f32 v147, v94, v95
	v_add_f32_e32 v204, v252, v82
	v_max_f32_e32 v80, v128, v129
	v_max3_f32 v81, v130, v131, v132
	v_max3_f32 v80, v80, v134, v135
	v_max3_f32 v81, v81, v133, v136
	v_max3_f32 v80, v80, v138, v139
	v_max3_f32 v81, v81, v137, v140
	v_max3_f32 v80, v80, v142, v143
	s_nop 0
	v_max3_f32 v81, v81, v141, v113
	v_max3_f32 v80, v80, v112, v114
	v_max3_f32 v81, v81, v115, v116
	v_max3_f32 v80, v80, v118, v119
	v_max3_f32 v81, v81, v117, v120
	v_max3_f32 v80, v80, v122, v123
	v_max3_f32 v81, v81, v121, v124
	v_max3_f32 v80, v80, v126, v127
	v_max3_f32 v80, v80, v125, v81
	v_mov_b32_e32 v81, v80
	s_nop 1
	v_permlane32_swap_b32_e32 v80, v81
	v_max_f32_e32 v80, v80, v81
	v_cmp_lt_f32_e32 vcc, s29, v80
	s_cmp_lg_u64 vcc, 0
	s_cselect_b64 s[42:43], -1, 0
	s_cbranch_vccnz .LBB0_729

.LBB0_724:
	s_add_i32 s42, s61, 0x2000
	s_cmpk_lg_i32 s61, 0x4000
	s_cselect_b32 s65, s42, 0
	s_movk_i32 s42, 0xff80
	s_mov_b32 s43, -1
	v_lshl_add_u64 v[110:111], v[212:213], 0, s[42:43]
	s_lshl_b32 s42, s65, 1
	s_add_i32 s42, s42, s60
	s_mov_b32 m0, s42
	s_nop 0
	global_load_lds_dwordx4 v[110:111], off
	s_addk_i32 s42, 0x2000
	s_mov_b32 m0, s42
	s_nop 0
	global_load_lds_dwordx4 v[212:213], off
	s_add_i32 s42, s61, s49
	s_mov_b32 m0, s42
	s_nop 0
	global_load_lds_dwordx4 v[214:215], off
	v_mfma_f32_32x32x16_bf16 v[96:111], v[80:83], v[172:175], v[64:79]
	v_add_f32_e32 v84, v128, v129
	v_add_f32_e32 v84, v130, v84
	v_add_f32_e32 v84, v131, v84
	v_add_f32_e32 v84, v132, v84
	v_add_f32_e32 v84, v133, v84
	v_cvt_pk_bf16_f32 v160, v128, v129
	v_cvt_pk_bf16_f32 v161, v130, v131
	v_add_f32_e32 v80, v134, v84
	v_add_f32_e32 v80, v135, v80
	v_add_f32_e32 v80, v136, v80
	v_add_f32_e32 v128, v137, v80
	v_mfma_f32_32x32x16_bf16 v[80:95], v[196:199], v[172:175], v[64:79]
	v_cvt_pk_bf16_f32 v162, v132, v133
	v_cvt_pk_bf16_f32 v163, v134, v135
	v_mfma_f32_32x32x16_bf16 v[96:111], v[200:203], v[168:171], v[96:111]
	v_add_f32_e32 v128, v138, v128
	v_add_f32_e32 v128, v139, v128
	v_add_f32_e32 v128, v140, v128
	v_add_f32_e32 v128, v141, v128
	v_cvt_pk_bf16_f32 v152, v136, v137
	v_cvt_pk_bf16_f32 v153, v138, v139
	v_mfma_f32_32x32x16_bf16 v[80:95], v[192:195], v[168:171], v[80:95]
	v_add_f32_e32 v128, v142, v128
	v_add_f32_e32 v128, v143, v128
	v_add_f32_e32 v128, v112, v128
	v_add_f32_e32 v128, v113, v128
	v_cvt_pk_bf16_f32 v154, v140, v141
	v_cvt_pk_bf16_f32 v155, v142, v143
	v_mfma_f32_32x32x16_bf16 v[96:111], v[188:191], v[164:167], v[96:111]
	v_add_f32_e32 v128, v114, v128
	v_add_f32_e32 v128, v115, v128
	v_add_f32_e32 v128, v116, v128
	v_add_f32_e32 v128, v117, v128
	v_cvt_pk_bf16_f32 v148, v112, v113
	v_cvt_pk_bf16_f32 v149, v114, v115
	v_mfma_f32_32x32x16_bf16 v[80:95], v[184:187], v[164:167], v[80:95]
	v_add_f32_e32 v112, v118, v128
	v_add_f32_e32 v112, v119, v112
	v_add_f32_e32 v112, v120, v112
	v_add_f32_e32 v112, v121, v112
	v_cvt_pk_bf16_f32 v150, v116, v117
	v_cvt_pk_bf16_f32 v151, v118, v119
	v_mfma_f32_32x32x16_bf16 v[96:111], v[180:183], v[156:159], v[96:111]
	v_add_f32_e32 v112, v122, v112
	v_add_f32_e32 v112, v123, v112
	v_add_f32_e32 v112, v124, v112
	v_add_f32_e32 v112, v125, v112
	v_cvt_pk_bf16_f32 v144, v120, v121
	v_cvt_pk_bf16_f32 v145, v122, v123
	v_mfma_f32_32x32x16_bf16 v[80:95], v[176:179], v[156:159], v[80:95]
	v_add_f32_e32 v112, v126, v112
	v_add_f32_e32 v114, v127, v112
	v_cvt_pk_bf16_f32 v146, v124, v125
	v_cvt_pk_bf16_f32 v147, v126, v127
	v_add_f32_e32 v252, v204, v114
	v_max_f32_e32 v112, v96, v97
	v_max3_f32 v113, v98, v99, v100
	v_max3_f32 v112, v112, v102, v103
	v_max3_f32 v113, v113, v101, v104
	v_max3_f32 v112, v112, v106, v107
	v_max3_f32 v113, v113, v105, v108
	v_max3_f32 v112, v112, v110, v111
	s_nop 0
	v_max3_f32 v113, v113, v109, v81
	v_max3_f32 v112, v112, v80, v82
	v_max3_f32 v113, v113, v83, v84
	v_max3_f32 v112, v112, v86, v87
	v_max3_f32 v113, v113, v85, v88
	v_max3_f32 v112, v112, v90, v91
	v_max3_f32 v113, v113, v89, v92
	v_max3_f32 v112, v112, v94, v95
	v_max3_f32 v112, v112, v93, v113
	v_mov_b32_e32 v113, v112
	s_nop 1
	v_permlane32_swap_b32_e32 v112, v113
	v_max_f32_e32 v112, v112, v113
	v_cmp_lt_f32_e32 vcc, s29, v112
	s_cmp_lg_u64 vcc, 0
	s_cselect_b64 s[42:43], -1, 0
	s_cbranch_vccnz .LBB0_732
